# GEMM epilogues: bf16 pack + v_permlane16_swap lane exchange, dwordx4 stores (plain + up/silu), same math
# speedup vs baseline: 1.0239x; 1.0239x over previous
; __device__ __forceinline__ unsigned pk2(float lo, float hi) { const f32x2v v = {lo, hi}; const bf16x2v r = __builtin_convertvector(v, bf16x2v); return __builtin_bit_cast(unsigned, r); }
; #define GEMM_EPI_LOOP _Pragma("unroll") for (int ai = 0; ai < 2; ++ai) _Pragma("unroll") for (int m = 0; m < 4; ++m) _Pragma("unroll") for (int bj = 0; bj < 2; ++bj)
; __device__ __forceinline__ void gemm_bf16_phase(const bf16_t* A, int lda, const bf16_t* Bt, int K, int TN, bf16_t* out, int ldo, char* lds) {
;   gemm_phase(A, lda, Bt, K, K, TN, lds, [&](f32x4 (&acc)[2][2][4][2], int tm, int tn) {
;     GEMM_LANE;
;     GEMM_EPI_LOOP {
;       const int row = tm * 256 + ai * 128 + wr * 64 + m * 16 + fr;
; #pragma unroll
;       for (int n = 0; n < 2; ++n) {
;         u32x2 o; o.x = pk2(acc[ai][bj][m][n][0], acc[ai][bj][m][n][1]); o.y = pk2(acc[ai][bj][m][n][2], acc[ai][bj][m][n][3]);
;         *(u32x2*)(out + (size_t)row * ldo + tn * 256 + bj * 128 + wc * 32 + n * 16 + 4 * fq) = o;
;       }
;     }
;   });
.LBB0_96:
	s_mul_i32 s16, s36, 0x80000
	s_lshl_b32 s17, s30, 9
	s_add_u32 s16, s16, s17
	v_cvt_pk_bf16_f32 v116, v116, v117
	v_cvt_pk_bf16_f32 v117, v118, v119
	v_cvt_pk_bf16_f32 v118, v112, v113
	v_cvt_pk_bf16_f32 v119, v114, v115
	v_cvt_pk_bf16_f32 v124, v124, v125
	v_cvt_pk_bf16_f32 v125, v126, v127
	v_cvt_pk_bf16_f32 v126, v120, v121
	v_cvt_pk_bf16_f32 v127, v122, v123
	v_cvt_pk_bf16_f32 v100, v100, v101
	v_cvt_pk_bf16_f32 v101, v102, v103
	v_cvt_pk_bf16_f32 v102, v96, v97
	v_cvt_pk_bf16_f32 v103, v98, v99
	v_cvt_pk_bf16_f32 v108, v108, v109
	v_cvt_pk_bf16_f32 v109, v110, v111
	v_cvt_pk_bf16_f32 v110, v104, v105
	v_cvt_pk_bf16_f32 v111, v106, v107
	v_cvt_pk_bf16_f32 v84, v84, v85
	v_cvt_pk_bf16_f32 v85, v86, v87
	v_cvt_pk_bf16_f32 v86, v76, v77
	v_cvt_pk_bf16_f32 v87, v78, v79
	v_cvt_pk_bf16_f32 v92, v92, v93
	v_cvt_pk_bf16_f32 v93, v94, v95
	v_cvt_pk_bf16_f32 v94, v88, v89
	v_cvt_pk_bf16_f32 v95, v90, v91
	v_cvt_pk_bf16_f32 v52, v52, v53
	v_cvt_pk_bf16_f32 v53, v54, v55
	v_cvt_pk_bf16_f32 v54, v44, v45
	v_cvt_pk_bf16_f32 v55, v46, v47
	v_cvt_pk_bf16_f32 v64, v64, v65
	v_cvt_pk_bf16_f32 v65, v66, v67
	v_cvt_pk_bf16_f32 v66, v60, v61
	v_cvt_pk_bf16_f32 v67, v62, v63
	v_cvt_pk_bf16_f32 v68, v68, v69
	v_cvt_pk_bf16_f32 v69, v70, v71
	v_cvt_pk_bf16_f32 v70, v56, v57
	v_cvt_pk_bf16_f32 v71, v58, v59
	v_cvt_pk_bf16_f32 v80, v80, v81
	v_cvt_pk_bf16_f32 v81, v82, v83
	v_cvt_pk_bf16_f32 v82, v72, v73
	v_cvt_pk_bf16_f32 v83, v74, v75
	v_cvt_pk_bf16_f32 v36, v36, v37
	v_cvt_pk_bf16_f32 v37, v38, v39
	v_cvt_pk_bf16_f32 v38, v32, v33
	v_cvt_pk_bf16_f32 v39, v34, v35
	v_cvt_pk_bf16_f32 v48, v48, v49
	v_cvt_pk_bf16_f32 v49, v50, v51
	v_cvt_pk_bf16_f32 v50, v40, v41
	v_cvt_pk_bf16_f32 v51, v42, v43
	v_cvt_pk_bf16_f32 v20, v20, v21
	v_cvt_pk_bf16_f32 v21, v22, v23
	v_cvt_pk_bf16_f32 v22, v16, v17
	v_cvt_pk_bf16_f32 v23, v18, v19
	v_cvt_pk_bf16_f32 v28, v28, v29
	v_cvt_pk_bf16_f32 v29, v30, v31
	v_cvt_pk_bf16_f32 v30, v24, v25
	v_cvt_pk_bf16_f32 v31, v26, v27
	v_cvt_pk_bf16_f32 v4, v4, v5
	v_cvt_pk_bf16_f32 v5, v6, v7
	v_cvt_pk_bf16_f32 v6, v0, v1
	v_cvt_pk_bf16_f32 v7, v2, v3
	v_cvt_pk_bf16_f32 v12, v12, v13
	v_cvt_pk_bf16_f32 v13, v14, v15
	v_cvt_pk_bf16_f32 v14, v8, v9
	v_cvt_pk_bf16_f32 v15, v10, v11
	s_add_u32 s30, s84, s16
	s_addc_u32 s31, s85, 0
	v_lshrrev_b32_e32 v131, 1, v179
	v_and_b32_e32 v130, 16, v131
	v_and_b32_e32 v131, 8, v131
	v_lshl_or_b32 v130, v131, 2, v130
	v_and_b32_e32 v131, 0xc0, v179
	v_or_b32_e32 v130, v130, v131
	v_ashrrev_i32_e32 v128, 2, v179
	v_and_b32_e32 v128, 0xffffffc0, v128
	v_and_or_b32 v128, v179, 15, v128
	v_lshl_or_b32 v128, v128, 11, v130
	v_permlane16_swap_b32_e32 v116, v118
	v_permlane16_swap_b32_e32 v117, v119
	v_permlane16_swap_b32_e32 v124, v126
	v_permlane16_swap_b32_e32 v125, v127
	v_permlane16_swap_b32_e32 v100, v102
	v_permlane16_swap_b32_e32 v101, v103
	v_permlane16_swap_b32_e32 v108, v110
	v_permlane16_swap_b32_e32 v109, v111
	v_permlane16_swap_b32_e32 v84, v86
	v_permlane16_swap_b32_e32 v85, v87
	v_permlane16_swap_b32_e32 v92, v94
	v_permlane16_swap_b32_e32 v93, v95
	v_permlane16_swap_b32_e32 v52, v54
	v_permlane16_swap_b32_e32 v53, v55
	v_permlane16_swap_b32_e32 v64, v66
	v_permlane16_swap_b32_e32 v65, v67
	v_permlane16_swap_b32_e32 v68, v70
	v_permlane16_swap_b32_e32 v69, v71
	v_permlane16_swap_b32_e32 v80, v82
	v_permlane16_swap_b32_e32 v81, v83
	v_permlane16_swap_b32_e32 v36, v38
	v_permlane16_swap_b32_e32 v37, v39
	v_permlane16_swap_b32_e32 v48, v50
	v_permlane16_swap_b32_e32 v49, v51
	v_permlane16_swap_b32_e32 v20, v22
	v_permlane16_swap_b32_e32 v21, v23
	v_permlane16_swap_b32_e32 v28, v30
	v_permlane16_swap_b32_e32 v29, v31
	v_permlane16_swap_b32_e32 v4, v6
	v_permlane16_swap_b32_e32 v5, v7
	v_permlane16_swap_b32_e32 v12, v14
	v_permlane16_swap_b32_e32 v13, v15
	global_store_dwordx4 v128, v[116:119], s[30:31]
	global_store_dwordx4 v128, v[124:127], s[30:31] offset:256
	v_add_u32_e32 v129, 0x8000, v128
	global_store_dwordx4 v129, v[100:103], s[30:31]
	global_store_dwordx4 v129, v[108:111], s[30:31] offset:256
	v_add_u32_e32 v130, 0x10000, v128
	global_store_dwordx4 v130, v[84:87], s[30:31]
	global_store_dwordx4 v130, v[92:95], s[30:31] offset:256
	v_add_u32_e32 v129, 0x18000, v128
	global_store_dwordx4 v129, v[52:55], s[30:31]
	global_store_dwordx4 v129, v[64:67], s[30:31] offset:256
	v_add_u32_e32 v130, 0x40000, v128
	global_store_dwordx4 v130, v[68:71], s[30:31]
	global_store_dwordx4 v130, v[80:83], s[30:31] offset:256
	v_add_u32_e32 v129, 0x48000, v128
	global_store_dwordx4 v129, v[36:39], s[30:31]
	global_store_dwordx4 v129, v[48:51], s[30:31] offset:256
	v_add_u32_e32 v130, 0x50000, v128
	global_store_dwordx4 v130, v[20:23], s[30:31]
	global_store_dwordx4 v130, v[28:31], s[30:31] offset:256
	v_add_u32_e32 v129, 0x58000, v128
	global_store_dwordx4 v129, v[4:7], s[30:31]
	global_store_dwordx4 v129, v[12:15], s[30:31] offset:256
	s_andn2_b64 vcc, exec, s[94:95]
	s_mov_b32 s30, s38
	s_mov_b32 s36, s42
	s_nop 1
	s_cbranch_vccz .LBB0_109

; __device__ __forceinline__ unsigned pk2(float lo, float hi) { const f32x2v v = {lo, hi}; const bf16x2v r = __builtin_convertvector(v, bf16x2v); return __builtin_bit_cast(unsigned, r); }
; #define GEMM_EPI_LOOP _Pragma("unroll") for (int ai = 0; ai < 2; ++ai) _Pragma("unroll") for (int m = 0; m < 4; ++m) _Pragma("unroll") for (int bj = 0; bj < 2; ++bj)
; __device__ __forceinline__ void gemm_bf16_phase(const bf16_t* A, int lda, const bf16_t* Bt, int K, int TN, bf16_t* out, int ldo, char* lds) {
;   gemm_phase(A, lda, Bt, K, K, TN, lds, [&](f32x4 (&acc)[2][2][4][2], int tm, int tn) {
;     GEMM_LANE;
;     GEMM_EPI_LOOP {
;       const int row = tm * 256 + ai * 128 + wr * 64 + m * 16 + fr;
; #pragma unroll
;       for (int n = 0; n < 2; ++n) {
;         u32x2 o; o.x = pk2(acc[ai][bj][m][n][0], acc[ai][bj][m][n][1]); o.y = pk2(acc[ai][bj][m][n][2], acc[ai][bj][m][n][3]);
;         *(u32x2*)(out + (size_t)row * ldo + tn * 256 + bj * 128 + wc * 32 + n * 16 + 4 * fq) = o;
;       }
;     }
;   });
.LBB0_146:
	s_mul_i32 s16, s30, 0x80000
	s_lshl_b32 s17, s34, 9
	s_add_u32 s16, s16, s17
	v_readlane_b32 s34, v252, 36
	v_readlane_b32 s35, v252, 37
	v_cvt_pk_bf16_f32 v120, v120, v121
	v_cvt_pk_bf16_f32 v121, v122, v123
	v_cvt_pk_bf16_f32 v122, v112, v113
	v_cvt_pk_bf16_f32 v123, v114, v115
	v_cvt_pk_bf16_f32 v124, v124, v125
	v_cvt_pk_bf16_f32 v125, v126, v127
	v_cvt_pk_bf16_f32 v126, v116, v117
	v_cvt_pk_bf16_f32 v127, v118, v119
	v_cvt_pk_bf16_f32 v100, v100, v101
	v_cvt_pk_bf16_f32 v101, v102, v103
	v_cvt_pk_bf16_f32 v102, v96, v97
	v_cvt_pk_bf16_f32 v103, v98, v99
	v_cvt_pk_bf16_f32 v108, v108, v109
	v_cvt_pk_bf16_f32 v109, v110, v111
	v_cvt_pk_bf16_f32 v110, v104, v105
	v_cvt_pk_bf16_f32 v111, v106, v107
	v_cvt_pk_bf16_f32 v84, v84, v85
	v_cvt_pk_bf16_f32 v85, v86, v87
	v_cvt_pk_bf16_f32 v86, v76, v77
	v_cvt_pk_bf16_f32 v87, v78, v79
	v_cvt_pk_bf16_f32 v92, v92, v93
	v_cvt_pk_bf16_f32 v93, v94, v95
	v_cvt_pk_bf16_f32 v94, v88, v89
	v_cvt_pk_bf16_f32 v95, v90, v91
	v_cvt_pk_bf16_f32 v52, v52, v53
	v_cvt_pk_bf16_f32 v53, v54, v55
	v_cvt_pk_bf16_f32 v54, v44, v45
	v_cvt_pk_bf16_f32 v55, v46, v47
	v_cvt_pk_bf16_f32 v64, v64, v65
	v_cvt_pk_bf16_f32 v65, v66, v67
	v_cvt_pk_bf16_f32 v66, v60, v61
	v_cvt_pk_bf16_f32 v67, v62, v63
	v_cvt_pk_bf16_f32 v68, v68, v69
	v_cvt_pk_bf16_f32 v69, v70, v71
	v_cvt_pk_bf16_f32 v70, v56, v57
	v_cvt_pk_bf16_f32 v71, v58, v59
	v_cvt_pk_bf16_f32 v80, v80, v81
	v_cvt_pk_bf16_f32 v81, v82, v83
	v_cvt_pk_bf16_f32 v82, v72, v73
	v_cvt_pk_bf16_f32 v83, v74, v75
	v_cvt_pk_bf16_f32 v36, v36, v37
	v_cvt_pk_bf16_f32 v37, v38, v39
	v_cvt_pk_bf16_f32 v38, v32, v33
	v_cvt_pk_bf16_f32 v39, v34, v35
	v_cvt_pk_bf16_f32 v48, v48, v49
	v_cvt_pk_bf16_f32 v49, v50, v51
	v_cvt_pk_bf16_f32 v50, v40, v41
	v_cvt_pk_bf16_f32 v51, v42, v43
	v_cvt_pk_bf16_f32 v20, v20, v21
	v_cvt_pk_bf16_f32 v21, v22, v23
	v_cvt_pk_bf16_f32 v22, v16, v17
	v_cvt_pk_bf16_f32 v23, v18, v19
	v_cvt_pk_bf16_f32 v28, v28, v29
	v_cvt_pk_bf16_f32 v29, v30, v31
	v_cvt_pk_bf16_f32 v30, v24, v25
	v_cvt_pk_bf16_f32 v31, v26, v27
	v_cvt_pk_bf16_f32 v8, v8, v9
	v_cvt_pk_bf16_f32 v9, v10, v11
	v_cvt_pk_bf16_f32 v10, v0, v1
	v_cvt_pk_bf16_f32 v11, v2, v3
	v_cvt_pk_bf16_f32 v12, v12, v13
	v_cvt_pk_bf16_f32 v13, v14, v15
	v_cvt_pk_bf16_f32 v14, v4, v5
	v_cvt_pk_bf16_f32 v15, v6, v7
	s_add_u32 s34, s34, s16
	s_addc_u32 s35, s35, 0
	v_lshrrev_b32_e32 v131, 1, v179
	v_and_b32_e32 v130, 16, v131
	v_and_b32_e32 v131, 8, v131
	v_lshl_or_b32 v130, v131, 2, v130
	v_and_b32_e32 v131, 0xc0, v179
	v_or_b32_e32 v130, v130, v131
	v_ashrrev_i32_e32 v128, 2, v179
	v_and_b32_e32 v128, 0xffffffc0, v128
	v_and_or_b32 v128, v179, 15, v128
	v_lshl_or_b32 v128, v128, 11, v130
	v_permlane16_swap_b32_e32 v120, v122
	v_permlane16_swap_b32_e32 v121, v123
	v_permlane16_swap_b32_e32 v124, v126
	v_permlane16_swap_b32_e32 v125, v127
	v_permlane16_swap_b32_e32 v100, v102
	v_permlane16_swap_b32_e32 v101, v103
	v_permlane16_swap_b32_e32 v108, v110
	v_permlane16_swap_b32_e32 v109, v111
	v_permlane16_swap_b32_e32 v84, v86
	v_permlane16_swap_b32_e32 v85, v87
	v_permlane16_swap_b32_e32 v92, v94
	v_permlane16_swap_b32_e32 v93, v95
	v_permlane16_swap_b32_e32 v52, v54
	v_permlane16_swap_b32_e32 v53, v55
	v_permlane16_swap_b32_e32 v64, v66
	v_permlane16_swap_b32_e32 v65, v67
	v_permlane16_swap_b32_e32 v68, v70
	v_permlane16_swap_b32_e32 v69, v71
	v_permlane16_swap_b32_e32 v80, v82
	v_permlane16_swap_b32_e32 v81, v83
	v_permlane16_swap_b32_e32 v36, v38
	v_permlane16_swap_b32_e32 v37, v39
	v_permlane16_swap_b32_e32 v48, v50
	v_permlane16_swap_b32_e32 v49, v51
	v_permlane16_swap_b32_e32 v20, v22
	v_permlane16_swap_b32_e32 v21, v23
	v_permlane16_swap_b32_e32 v28, v30
	v_permlane16_swap_b32_e32 v29, v31
	v_permlane16_swap_b32_e32 v8, v10
	v_permlane16_swap_b32_e32 v9, v11
	v_permlane16_swap_b32_e32 v12, v14
	v_permlane16_swap_b32_e32 v13, v15
	global_store_dwordx4 v128, v[120:123], s[34:35]
	global_store_dwordx4 v128, v[124:127], s[34:35] offset:256
	v_add_u32_e32 v129, 0x8000, v128
	global_store_dwordx4 v129, v[100:103], s[34:35]
	global_store_dwordx4 v129, v[108:111], s[34:35] offset:256
	v_add_u32_e32 v130, 0x10000, v128
	global_store_dwordx4 v130, v[84:87], s[34:35]
	global_store_dwordx4 v130, v[92:95], s[34:35] offset:256
	v_add_u32_e32 v129, 0x18000, v128
	global_store_dwordx4 v129, v[52:55], s[34:35]
	global_store_dwordx4 v129, v[64:67], s[34:35] offset:256
	v_add_u32_e32 v130, 0x40000, v128
	global_store_dwordx4 v130, v[68:71], s[34:35]
	global_store_dwordx4 v130, v[80:83], s[34:35] offset:256
	v_add_u32_e32 v129, 0x48000, v128
	global_store_dwordx4 v129, v[36:39], s[34:35]
	global_store_dwordx4 v129, v[48:51], s[34:35] offset:256
	v_add_u32_e32 v130, 0x50000, v128
	global_store_dwordx4 v130, v[20:23], s[34:35]
	global_store_dwordx4 v130, v[28:31], s[34:35] offset:256
	v_add_u32_e32 v129, 0x58000, v128
	global_store_dwordx4 v129, v[8:11], s[34:35]
	global_store_dwordx4 v129, v[12:15], s[34:35] offset:256
	s_andn2_b64 vcc, exec, s[42:43]
	s_mov_b32 s34, s36
	s_mov_b32 s30, s38
	s_nop 1
	s_cbranch_vccz .LBB0_161

; __device__ __forceinline__ unsigned pk2(float lo, float hi) { const f32x2v v = {lo, hi}; const bf16x2v r = __builtin_convertvector(v, bf16x2v); return __builtin_bit_cast(unsigned, r); }
; #define GEMM_EPI_LOOP _Pragma("unroll") for (int ai = 0; ai < 2; ++ai) _Pragma("unroll") for (int m = 0; m < 4; ++m) _Pragma("unroll") for (int bj = 0; bj < 2; ++bj)
; __device__ __forceinline__ void gemm_bf16_phase(const bf16_t* A, int lda, const bf16_t* Bt, int K, int TN, bf16_t* out, int ldo, char* lds) {
;   gemm_phase(A, lda, Bt, K, K, TN, lds, [&](f32x4 (&acc)[2][2][4][2], int tm, int tn) {
;     GEMM_LANE;
;     GEMM_EPI_LOOP {
;       const int row = tm * 256 + ai * 128 + wr * 64 + m * 16 + fr;
; #pragma unroll
;       for (int n = 0; n < 2; ++n) {
;         u32x2 o; o.x = pk2(acc[ai][bj][m][n][0], acc[ai][bj][m][n][1]); o.y = pk2(acc[ai][bj][m][n][2], acc[ai][bj][m][n][3]);
;         *(u32x2*)(out + (size_t)row * ldo + tn * 256 + bj * 128 + wc * 32 + n * 16 + 4 * fq) = o;
;       }
;     }
;   });
.LBB0_580:
	s_mul_i32 s16, s34, 0x140000
	s_lshl_b32 s17, s0, 9
	s_add_u32 s16, s16, s17
	v_cvt_pk_bf16_f32 v116, v116, v117
	v_cvt_pk_bf16_f32 v117, v118, v119
	v_cvt_pk_bf16_f32 v118, v112, v113
	v_cvt_pk_bf16_f32 v119, v114, v115
	v_cvt_pk_bf16_f32 v124, v124, v125
	v_cvt_pk_bf16_f32 v125, v126, v127
	v_cvt_pk_bf16_f32 v126, v120, v121
	v_cvt_pk_bf16_f32 v127, v122, v123
	v_cvt_pk_bf16_f32 v100, v100, v101
	v_cvt_pk_bf16_f32 v101, v102, v103
	v_cvt_pk_bf16_f32 v102, v96, v97
	v_cvt_pk_bf16_f32 v103, v98, v99
	v_cvt_pk_bf16_f32 v108, v108, v109
	v_cvt_pk_bf16_f32 v109, v110, v111
	v_cvt_pk_bf16_f32 v110, v104, v105
	v_cvt_pk_bf16_f32 v111, v106, v107
	v_cvt_pk_bf16_f32 v80, v80, v81
	v_cvt_pk_bf16_f32 v81, v82, v83
	v_cvt_pk_bf16_f32 v82, v68, v69
	v_cvt_pk_bf16_f32 v83, v70, v71
	v_cvt_pk_bf16_f32 v92, v92, v93
	v_cvt_pk_bf16_f32 v93, v94, v95
	v_cvt_pk_bf16_f32 v94, v88, v89
	v_cvt_pk_bf16_f32 v95, v90, v91
	v_cvt_pk_bf16_f32 v48, v48, v49
	v_cvt_pk_bf16_f32 v49, v50, v51
	v_cvt_pk_bf16_f32 v50, v36, v37
	v_cvt_pk_bf16_f32 v51, v38, v39
	v_cvt_pk_bf16_f32 v64, v64, v65
	v_cvt_pk_bf16_f32 v65, v66, v67
	v_cvt_pk_bf16_f32 v66, v56, v57
	v_cvt_pk_bf16_f32 v67, v58, v59
	v_cvt_pk_bf16_f32 v72, v72, v73
	v_cvt_pk_bf16_f32 v73, v74, v75
	v_cvt_pk_bf16_f32 v74, v60, v61
	v_cvt_pk_bf16_f32 v75, v62, v63
	v_cvt_pk_bf16_f32 v84, v84, v85
	v_cvt_pk_bf16_f32 v85, v86, v87
	v_cvt_pk_bf16_f32 v86, v76, v77
	v_cvt_pk_bf16_f32 v87, v78, v79
	v_cvt_pk_bf16_f32 v40, v40, v41
	v_cvt_pk_bf16_f32 v41, v42, v43
	v_cvt_pk_bf16_f32 v42, v32, v33
	v_cvt_pk_bf16_f32 v43, v34, v35
	v_cvt_pk_bf16_f32 v52, v52, v53
	v_cvt_pk_bf16_f32 v53, v54, v55
	v_cvt_pk_bf16_f32 v54, v44, v45
	v_cvt_pk_bf16_f32 v55, v46, v47
	v_cvt_pk_bf16_f32 v20, v20, v21
	v_cvt_pk_bf16_f32 v21, v22, v23
	v_cvt_pk_bf16_f32 v22, v16, v17
	v_cvt_pk_bf16_f32 v23, v18, v19
	v_cvt_pk_bf16_f32 v28, v28, v29
	v_cvt_pk_bf16_f32 v29, v30, v31
	v_cvt_pk_bf16_f32 v30, v24, v25
	v_cvt_pk_bf16_f32 v31, v26, v27
	v_cvt_pk_bf16_f32 v4, v4, v5
	v_cvt_pk_bf16_f32 v5, v6, v7
	v_cvt_pk_bf16_f32 v6, v0, v1
	v_cvt_pk_bf16_f32 v7, v2, v3
	v_cvt_pk_bf16_f32 v12, v12, v13
	v_cvt_pk_bf16_f32 v13, v14, v15
	v_cvt_pk_bf16_f32 v14, v8, v9
	v_cvt_pk_bf16_f32 v15, v10, v11
	s_add_u32 s0, s84, s16
	s_addc_u32 s1, s85, 0
	v_lshrrev_b32_e32 v131, 1, v179
	v_and_b32_e32 v130, 16, v131
	v_and_b32_e32 v131, 8, v131
	v_lshl_or_b32 v130, v131, 2, v130
	v_and_b32_e32 v131, 0xc0, v179
	v_or_b32_e32 v130, v130, v131
	v_ashrrev_i32_e32 v128, 2, v179
	v_and_b32_e32 v128, 0xffffffc0, v128
	v_and_or_b32 v128, v179, 15, v128
	v_mul_u32_u24_e32 v128, 0x1400, v128
	v_add_u32_e32 v128, v128, v130
	v_permlane16_swap_b32_e32 v116, v118
	v_permlane16_swap_b32_e32 v117, v119
	v_permlane16_swap_b32_e32 v124, v126
	v_permlane16_swap_b32_e32 v125, v127
	v_permlane16_swap_b32_e32 v100, v102
	v_permlane16_swap_b32_e32 v101, v103
	v_permlane16_swap_b32_e32 v108, v110
	v_permlane16_swap_b32_e32 v109, v111
	v_permlane16_swap_b32_e32 v80, v82
	v_permlane16_swap_b32_e32 v81, v83
	v_permlane16_swap_b32_e32 v92, v94
	v_permlane16_swap_b32_e32 v93, v95
	v_permlane16_swap_b32_e32 v48, v50
	v_permlane16_swap_b32_e32 v49, v51
	v_permlane16_swap_b32_e32 v64, v66
	v_permlane16_swap_b32_e32 v65, v67
	v_permlane16_swap_b32_e32 v72, v74
	v_permlane16_swap_b32_e32 v73, v75
	v_permlane16_swap_b32_e32 v84, v86
	v_permlane16_swap_b32_e32 v85, v87
	v_permlane16_swap_b32_e32 v40, v42
	v_permlane16_swap_b32_e32 v41, v43
	v_permlane16_swap_b32_e32 v52, v54
	v_permlane16_swap_b32_e32 v53, v55
	v_permlane16_swap_b32_e32 v20, v22
	v_permlane16_swap_b32_e32 v21, v23
	v_permlane16_swap_b32_e32 v28, v30
	v_permlane16_swap_b32_e32 v29, v31
	v_permlane16_swap_b32_e32 v4, v6
	v_permlane16_swap_b32_e32 v5, v7
	v_permlane16_swap_b32_e32 v12, v14
	v_permlane16_swap_b32_e32 v13, v15
	global_store_dwordx4 v128, v[116:119], s[0:1]
	global_store_dwordx4 v128, v[124:127], s[0:1] offset:256
	v_add_u32_e32 v129, 0x14000, v128
	global_store_dwordx4 v129, v[100:103], s[0:1]
	global_store_dwordx4 v129, v[108:111], s[0:1] offset:256
	v_add_u32_e32 v130, 0x28000, v128
	global_store_dwordx4 v130, v[80:83], s[0:1]
	global_store_dwordx4 v130, v[92:95], s[0:1] offset:256
	v_add_u32_e32 v129, 0x3c000, v128
	global_store_dwordx4 v129, v[48:51], s[0:1]
	global_store_dwordx4 v129, v[64:67], s[0:1] offset:256
	v_add_u32_e32 v130, 0xa0000, v128
	global_store_dwordx4 v130, v[72:75], s[0:1]
	global_store_dwordx4 v130, v[84:87], s[0:1] offset:256
	v_add_u32_e32 v129, 0xb4000, v128
	global_store_dwordx4 v129, v[40:43], s[0:1]
	global_store_dwordx4 v129, v[52:55], s[0:1] offset:256
	v_add_u32_e32 v130, 0xc8000, v128
	global_store_dwordx4 v130, v[20:23], s[0:1]
	global_store_dwordx4 v130, v[28:31], s[0:1] offset:256
	v_add_u32_e32 v129, 0xdc000, v128
	global_store_dwordx4 v129, v[4:7], s[0:1]
	global_store_dwordx4 v129, v[12:15], s[0:1] offset:256
	s_andn2_b64 vcc, exec, s[38:39]
	s_mov_b32 s0, s30
	s_mov_b32 s34, s36
	s_nop 1
	s_cbranch_vccz .LBB0_595

; __device__ __forceinline__ unsigned pk2(float lo, float hi) { const f32x2v v = {lo, hi}; const bf16x2v r = __builtin_convertvector(v, bf16x2v); return __builtin_bit_cast(unsigned, r); }
; #define GEMM_EPI_LOOP _Pragma("unroll") for (int ai = 0; ai < 2; ++ai) _Pragma("unroll") for (int m = 0; m < 4; ++m) _Pragma("unroll") for (int bj = 0; bj < 2; ++bj)
; __device__ __forceinline__ void gemm_bf16_phase(const bf16_t* A, int lda, const bf16_t* Bt, int K, int TN, bf16_t* out, int ldo, char* lds) {
;   gemm_phase(A, lda, Bt, K, K, TN, lds, [&](f32x4 (&acc)[2][2][4][2], int tm, int tn) {
;     GEMM_LANE;
;     GEMM_EPI_LOOP {
;       const int row = tm * 256 + ai * 128 + wr * 64 + m * 16 + fr;
; #pragma unroll
;       for (int n = 0; n < 2; ++n) {
;         u32x2 o; o.x = pk2(acc[ai][bj][m][n][0], acc[ai][bj][m][n][1]); o.y = pk2(acc[ai][bj][m][n][2], acc[ai][bj][m][n][3]);
;         *(u32x2*)(out + (size_t)row * ldo + tn * 256 + bj * 128 + wc * 32 + n * 16 + 4 * fq) = o;
;       }
;     }
;   });
.LBB0_618:
	s_mul_i32 s34, s62, 0x80000
	s_lshl_b32 s17, s46, 9
	s_add_u32 s34, s34, s17
	v_readlane_b32 s64, v252, 36
	v_readlane_b32 s65, v252, 37
	v_cvt_pk_bf16_f32 v120, v120, v121
	v_cvt_pk_bf16_f32 v121, v122, v123
	v_cvt_pk_bf16_f32 v122, v112, v113
	v_cvt_pk_bf16_f32 v123, v114, v115
	v_cvt_pk_bf16_f32 v124, v124, v125
	v_cvt_pk_bf16_f32 v125, v126, v127
	v_cvt_pk_bf16_f32 v126, v116, v117
	v_cvt_pk_bf16_f32 v127, v118, v119
	v_cvt_pk_bf16_f32 v100, v100, v101
	v_cvt_pk_bf16_f32 v101, v102, v103
	v_cvt_pk_bf16_f32 v102, v96, v97
	v_cvt_pk_bf16_f32 v103, v98, v99
	v_cvt_pk_bf16_f32 v108, v108, v109
	v_cvt_pk_bf16_f32 v109, v110, v111
	v_cvt_pk_bf16_f32 v110, v104, v105
	v_cvt_pk_bf16_f32 v111, v106, v107
	v_cvt_pk_bf16_f32 v84, v84, v85
	v_cvt_pk_bf16_f32 v85, v86, v87
	v_cvt_pk_bf16_f32 v86, v76, v77
	v_cvt_pk_bf16_f32 v87, v78, v79
	v_cvt_pk_bf16_f32 v92, v92, v93
	v_cvt_pk_bf16_f32 v93, v94, v95
	v_cvt_pk_bf16_f32 v94, v88, v89
	v_cvt_pk_bf16_f32 v95, v90, v91
	v_cvt_pk_bf16_f32 v52, v52, v53
	v_cvt_pk_bf16_f32 v53, v54, v55
	v_cvt_pk_bf16_f32 v54, v44, v45
	v_cvt_pk_bf16_f32 v55, v46, v47
	v_cvt_pk_bf16_f32 v64, v64, v65
	v_cvt_pk_bf16_f32 v65, v66, v67
	v_cvt_pk_bf16_f32 v66, v60, v61
	v_cvt_pk_bf16_f32 v67, v62, v63
	v_cvt_pk_bf16_f32 v68, v68, v69
	v_cvt_pk_bf16_f32 v69, v70, v71
	v_cvt_pk_bf16_f32 v70, v56, v57
	v_cvt_pk_bf16_f32 v71, v58, v59
	v_cvt_pk_bf16_f32 v80, v80, v81
	v_cvt_pk_bf16_f32 v81, v82, v83
	v_cvt_pk_bf16_f32 v82, v72, v73
	v_cvt_pk_bf16_f32 v83, v74, v75
	v_cvt_pk_bf16_f32 v36, v36, v37
	v_cvt_pk_bf16_f32 v37, v38, v39
	v_cvt_pk_bf16_f32 v38, v32, v33
	v_cvt_pk_bf16_f32 v39, v34, v35
	v_cvt_pk_bf16_f32 v48, v48, v49
	v_cvt_pk_bf16_f32 v49, v50, v51
	v_cvt_pk_bf16_f32 v50, v40, v41
	v_cvt_pk_bf16_f32 v51, v42, v43
	v_cvt_pk_bf16_f32 v20, v20, v21
	v_cvt_pk_bf16_f32 v21, v22, v23
	v_cvt_pk_bf16_f32 v22, v16, v17
	v_cvt_pk_bf16_f32 v23, v18, v19
	v_cvt_pk_bf16_f32 v28, v28, v29
	v_cvt_pk_bf16_f32 v29, v30, v31
	v_cvt_pk_bf16_f32 v30, v24, v25
	v_cvt_pk_bf16_f32 v31, v26, v27
	v_cvt_pk_bf16_f32 v8, v8, v9
	v_cvt_pk_bf16_f32 v9, v10, v11
	v_cvt_pk_bf16_f32 v10, v0, v1
	v_cvt_pk_bf16_f32 v11, v2, v3
	v_cvt_pk_bf16_f32 v12, v12, v13
	v_cvt_pk_bf16_f32 v13, v14, v15
	v_cvt_pk_bf16_f32 v14, v4, v5
	v_cvt_pk_bf16_f32 v15, v6, v7
	s_add_u32 s64, s64, s34
	s_addc_u32 s65, s65, 0
	v_lshrrev_b32_e32 v131, 1, v179
	v_and_b32_e32 v130, 16, v131
	v_and_b32_e32 v131, 8, v131
	v_lshl_or_b32 v130, v131, 2, v130
	v_and_b32_e32 v131, 0xc0, v179
	v_or_b32_e32 v130, v130, v131
	v_ashrrev_i32_e32 v128, 2, v179
	v_and_b32_e32 v128, 0xffffffc0, v128
	v_and_or_b32 v128, v179, 15, v128
	v_lshl_or_b32 v128, v128, 11, v130
	v_permlane16_swap_b32_e32 v120, v122
	v_permlane16_swap_b32_e32 v121, v123
	v_permlane16_swap_b32_e32 v124, v126
	v_permlane16_swap_b32_e32 v125, v127
	v_permlane16_swap_b32_e32 v100, v102
	v_permlane16_swap_b32_e32 v101, v103
	v_permlane16_swap_b32_e32 v108, v110
	v_permlane16_swap_b32_e32 v109, v111
	v_permlane16_swap_b32_e32 v84, v86
	v_permlane16_swap_b32_e32 v85, v87
	v_permlane16_swap_b32_e32 v92, v94
	v_permlane16_swap_b32_e32 v93, v95
	v_permlane16_swap_b32_e32 v52, v54
	v_permlane16_swap_b32_e32 v53, v55
	v_permlane16_swap_b32_e32 v64, v66
	v_permlane16_swap_b32_e32 v65, v67
	v_permlane16_swap_b32_e32 v68, v70
	v_permlane16_swap_b32_e32 v69, v71
	v_permlane16_swap_b32_e32 v80, v82
	v_permlane16_swap_b32_e32 v81, v83
	v_permlane16_swap_b32_e32 v36, v38
	v_permlane16_swap_b32_e32 v37, v39
	v_permlane16_swap_b32_e32 v48, v50
	v_permlane16_swap_b32_e32 v49, v51
	v_permlane16_swap_b32_e32 v20, v22
	v_permlane16_swap_b32_e32 v21, v23
	v_permlane16_swap_b32_e32 v28, v30
	v_permlane16_swap_b32_e32 v29, v31
	v_permlane16_swap_b32_e32 v8, v10
	v_permlane16_swap_b32_e32 v9, v11
	v_permlane16_swap_b32_e32 v12, v14
	v_permlane16_swap_b32_e32 v13, v15
	global_store_dwordx4 v128, v[120:123], s[64:65]
	global_store_dwordx4 v128, v[124:127], s[64:65] offset:256
	v_add_u32_e32 v129, 0x8000, v128
	global_store_dwordx4 v129, v[100:103], s[64:65]
	global_store_dwordx4 v129, v[108:111], s[64:65] offset:256
	v_add_u32_e32 v130, 0x10000, v128
	global_store_dwordx4 v130, v[84:87], s[64:65]
	global_store_dwordx4 v130, v[92:95], s[64:65] offset:256
	v_add_u32_e32 v129, 0x18000, v128
	global_store_dwordx4 v129, v[52:55], s[64:65]
	global_store_dwordx4 v129, v[64:67], s[64:65] offset:256
	v_add_u32_e32 v130, 0x40000, v128
	global_store_dwordx4 v130, v[68:71], s[64:65]
	global_store_dwordx4 v130, v[80:83], s[64:65] offset:256
	v_add_u32_e32 v129, 0x48000, v128
	global_store_dwordx4 v129, v[36:39], s[64:65]
	global_store_dwordx4 v129, v[48:51], s[64:65] offset:256
	v_add_u32_e32 v130, 0x50000, v128
	global_store_dwordx4 v130, v[20:23], s[64:65]
	global_store_dwordx4 v130, v[28:31], s[64:65] offset:256
	v_add_u32_e32 v129, 0x58000, v128
	global_store_dwordx4 v129, v[8:11], s[64:65]
	global_store_dwordx4 v129, v[12:15], s[64:65] offset:256
	s_andn2_b64 vcc, exec, s[30:31]
	s_mov_b32 s46, s63
	s_mov_b32 s62, s16
	s_nop 1
	s_cbranch_vccz .LBB0_633

; __device__ __forceinline__ unsigned pk2(float lo, float hi) { const f32x2v v = {lo, hi}; const bf16x2v r = __builtin_convertvector(v, bf16x2v); return __builtin_bit_cast(unsigned, r); }
; __device__ __forceinline__ float silu_f(float x) { return x * __builtin_amdgcn_rcpf(1.f + __expf(-x)); }
; #define GEMM_EPI_LOOP _Pragma("unroll") for (int ai = 0; ai < 2; ++ai) _Pragma("unroll") for (int m = 0; m < 4; ++m) _Pragma("unroll") for (int bj = 0; bj < 2; ++bj)
; __device__ __forceinline__ void gemm_up_phase(const bf16_t* a, const bf16_t* wgu, bf16_t* act, char* lds) {
;   gemm_phase(a, 1024, wgu, 1024, 1024, NGU / 256, lds, [&](f32x4 (&acc)[2][2][4][2], int tm, int tn) {
;     GEMM_LANE;
;     GEMM_EPI_LOOP {
;       const int row = tm * 256 + ai * 128 + wr * 64 + m * 16 + fr;
;       const int col = tn * 128 + bj * 64 + wc * 16 + 4 * fq;
;       const f32x4 g = acc[ai][bj][m][0], u = acc[ai][bj][m][1];
;       u32x2 o; o.x = pk2(silu_f(g[0]) * u[0], silu_f(g[1]) * u[1]); o.y = pk2(silu_f(g[2]) * u[2], silu_f(g[3]) * u[3]);
;       *(u32x2*)(act + (size_t)row * DFF + col) = o;
;     }
;   });
.LBB0_645:
	v_mov_b32 v129, v179
	s_lshl_b32 s1, s34, 8
	v_ashrrev_i32_e32 v128, 2, v129
	v_and_b32_e32 v128, 0xffffffc0, v128
	v_and_or_b32 v130, v129, 15, s1
	s_lshl_b32 s0, s0, 7
	v_lshrrev_b32_e32 v129, 2, v129
	v_add_u32_e32 v128, v130, v128
	v_and_or_b32 v130, v129, 56, s0
	v_and_b32_e32 v131, 16, v179
	v_lshl_or_b32 v130, v131, 2, v130
	v_mul_f32_e32 v129, 0xbfb8aa3b, v124
	v_exp_f32_e32 v129, v129
	v_ashrrev_i32_e32 v131, 31, v130
	s_andn2_b64 vcc, exec, s[38:39]
	s_mov_b32 s34, s36
	v_add_f32_e32 v129, 1.0, v129
	v_rcp_f32_e32 v132, v129
	v_mul_f32_e32 v129, 0xbfb8aa3b, v125
	v_exp_f32_e32 v129, v129
	s_nop 0
	v_add_f32_e32 v129, 1.0, v129
	v_rcp_f32_e32 v133, v129
	s_nop 0
	v_pk_mul_f32 v[124:125], v[124:125], v[132:133]
	s_nop 0
	v_pk_mul_f32 v[120:121], v[120:121], v[124:125]
	s_nop 0
	v_cvt_pk_bf16_f32 v124, v120, v121
	v_mul_f32_e32 v120, 0xbfb8aa3b, v126
	v_mul_f32_e32 v121, 0xbfb8aa3b, v127
	v_exp_f32_e32 v120, v120
	v_exp_f32_e32 v121, v121
	v_add_f32_e32 v120, 1.0, v120
	v_add_f32_e32 v121, 1.0, v121
	v_rcp_f32_e32 v120, v120
	v_rcp_f32_e32 v121, v121
	s_nop 0
	v_pk_mul_f32 v[120:121], v[126:127], v[120:121]
	s_nop 0
	v_pk_mul_f32 v[120:121], v[122:123], v[120:121]
	v_lshlrev_b64 v[122:123], 1, v[130:131]
	v_cvt_pk_bf16_f32 v125, v120, v121
	v_mov_b64_e32 v[120:121], s[84:85]
	v_mad_i64_i32 v[126:127], s[0:1], v128, s3, v[120:121]
	v_lshl_add_u64 v[126:127], v[126:127], 0, v[122:123]
	v_mov_b32_e32 v140, v124
	v_mov_b32_e32 v141, v125
	v_mul_f32_e32 v124, 0xbfb8aa3b, v116
	v_mul_f32_e32 v125, 0xbfb8aa3b, v117
	v_exp_f32_e32 v124, v124
	v_exp_f32_e32 v125, v125
	v_add_f32_e32 v124, 1.0, v124
	v_add_f32_e32 v125, 1.0, v125
	v_rcp_f32_e32 v124, v124
	v_rcp_f32_e32 v125, v125
	s_nop 0
	v_pk_mul_f32 v[116:117], v[116:117], v[124:125]
	s_nop 0
	v_pk_mul_f32 v[112:113], v[112:113], v[116:117]
	s_nop 0
	v_cvt_pk_bf16_f32 v112, v112, v113
	v_mul_f32_e32 v113, 0xbfb8aa3b, v118
	v_exp_f32_e32 v113, v113
	s_nop 0
	v_add_f32_e32 v113, 1.0, v113
	v_rcp_f32_e32 v116, v113
	v_mul_f32_e32 v113, 0xbfb8aa3b, v119
	v_exp_f32_e32 v113, v113
	s_nop 0
	v_add_f32_e32 v113, 1.0, v113
	v_rcp_f32_e32 v117, v113
	s_nop 0
	v_pk_mul_f32 v[116:117], v[118:119], v[116:117]
	s_nop 0
	v_pk_mul_f32 v[114:115], v[114:115], v[116:117]
	s_nop 0
	v_cvt_pk_bf16_f32 v113, v114, v115
	v_mov_b32_e32 v142, v112
	v_mov_b32_e32 v143, v113
	s_nop 1
	v_permlane16_swap_b32_e32 v140, v142
	v_permlane16_swap_b32_e32 v141, v143
	global_store_dwordx4 v[126:127], v[140:143], off
	v_mul_f32_e32 v112, 0xbfb8aa3b, v108
	v_mul_f32_e32 v113, 0xbfb8aa3b, v109
	v_exp_f32_e32 v112, v112
	v_exp_f32_e32 v113, v113
	v_or_b32_e32 v114, 16, v128
	v_add_f32_e32 v112, 1.0, v112
	v_add_f32_e32 v113, 1.0, v113
	v_rcp_f32_e32 v112, v112
	v_rcp_f32_e32 v113, v113
	s_nop 0
	v_pk_mul_f32 v[108:109], v[108:109], v[112:113]
	s_nop 0
	v_pk_mul_f32 v[104:105], v[104:105], v[108:109]
	s_nop 0
	v_cvt_pk_bf16_f32 v104, v104, v105
	v_mul_f32_e32 v105, 0xbfb8aa3b, v110
	v_exp_f32_e32 v105, v105
	s_nop 0
	v_add_f32_e32 v105, 1.0, v105
	v_rcp_f32_e32 v108, v105
	v_mul_f32_e32 v105, 0xbfb8aa3b, v111
	v_exp_f32_e32 v105, v105
	s_nop 0
	v_add_f32_e32 v105, 1.0, v105
	v_rcp_f32_e32 v109, v105
	s_nop 0
	v_pk_mul_f32 v[108:109], v[110:111], v[108:109]
	s_nop 0
	v_pk_mul_f32 v[106:107], v[106:107], v[108:109]
	s_nop 0
	v_cvt_pk_bf16_f32 v105, v106, v107
	v_mad_i64_i32 v[106:107], s[0:1], v114, s3, v[120:121]
	v_lshl_add_u64 v[106:107], v[106:107], 0, v[122:123]
	v_mov_b32_e32 v144, v104
	v_mov_b32_e32 v145, v105
	v_mul_f32_e32 v104, 0xbfb8aa3b, v100
	v_mul_f32_e32 v105, 0xbfb8aa3b, v101
	v_exp_f32_e32 v104, v104
	v_exp_f32_e32 v105, v105
	v_add_f32_e32 v104, 1.0, v104
	v_add_f32_e32 v105, 1.0, v105
	v_rcp_f32_e32 v104, v104
	v_rcp_f32_e32 v105, v105
	s_nop 0
	v_pk_mul_f32 v[100:101], v[100:101], v[104:105]
	s_nop 0
	v_pk_mul_f32 v[96:97], v[96:97], v[100:101]
	s_nop 0
	v_cvt_pk_bf16_f32 v96, v96, v97
	v_mul_f32_e32 v97, 0xbfb8aa3b, v102
	v_exp_f32_e32 v97, v97
	s_nop 0
	v_add_f32_e32 v97, 1.0, v97
	v_rcp_f32_e32 v100, v97
	v_mul_f32_e32 v97, 0xbfb8aa3b, v103
	v_exp_f32_e32 v97, v97
	s_nop 0
	v_add_f32_e32 v97, 1.0, v97
	v_rcp_f32_e32 v101, v97
	s_nop 0
	v_pk_mul_f32 v[100:101], v[102:103], v[100:101]
	s_nop 0
	v_pk_mul_f32 v[98:99], v[98:99], v[100:101]
	s_nop 0
	v_cvt_pk_bf16_f32 v97, v98, v99
	v_mov_b32_e32 v146, v96
	v_mov_b32_e32 v147, v97
	s_nop 1
	v_permlane16_swap_b32_e32 v144, v146
	v_permlane16_swap_b32_e32 v145, v147
	global_store_dwordx4 v[106:107], v[144:147], off
	v_mul_f32_e32 v96, 0xbfb8aa3b, v92
	v_mul_f32_e32 v97, 0xbfb8aa3b, v93
	v_exp_f32_e32 v96, v96
	v_exp_f32_e32 v97, v97
	v_or_b32_e32 v98, 32, v128
	v_add_f32_e32 v96, 1.0, v96
	v_add_f32_e32 v97, 1.0, v97
	v_rcp_f32_e32 v96, v96
	v_rcp_f32_e32 v97, v97
	s_nop 0
	v_pk_mul_f32 v[92:93], v[92:93], v[96:97]
	s_nop 0
	v_pk_mul_f32 v[88:89], v[88:89], v[92:93]
	s_nop 0
	v_cvt_pk_bf16_f32 v88, v88, v89
	v_mul_f32_e32 v89, 0xbfb8aa3b, v94
	v_exp_f32_e32 v89, v89
	s_nop 0
	v_add_f32_e32 v89, 1.0, v89
	v_rcp_f32_e32 v92, v89
	v_mul_f32_e32 v89, 0xbfb8aa3b, v95
	v_exp_f32_e32 v89, v89
	s_nop 0
	v_add_f32_e32 v89, 1.0, v89
	v_rcp_f32_e32 v93, v89
	s_nop 0
	v_pk_mul_f32 v[92:93], v[94:95], v[92:93]
	s_nop 0
	v_pk_mul_f32 v[90:91], v[90:91], v[92:93]
	s_nop 0
	v_cvt_pk_bf16_f32 v89, v90, v91
	v_mad_i64_i32 v[90:91], s[0:1], v98, s3, v[120:121]
	v_lshl_add_u64 v[90:91], v[90:91], 0, v[122:123]
	v_mov_b32_e32 v148, v88
	v_mov_b32_e32 v149, v89
	v_mul_f32_e32 v88, 0xbfb8aa3b, v84
	v_mul_f32_e32 v89, 0xbfb8aa3b, v85
	v_exp_f32_e32 v88, v88
	v_exp_f32_e32 v89, v89
	v_add_f32_e32 v88, 1.0, v88
	v_add_f32_e32 v89, 1.0, v89
	v_rcp_f32_e32 v88, v88
; __device__ __forceinline__ unsigned pk2(float lo, float hi) { const f32x2v v = {lo, hi}; const bf16x2v r = __builtin_convertvector(v, bf16x2v); return __builtin_bit_cast(unsigned, r); }
; __device__ __forceinline__ float silu_f(float x) { return x * __builtin_amdgcn_rcpf(1.f + __expf(-x)); }
; #define GEMM_EPI_LOOP _Pragma("unroll") for (int ai = 0; ai < 2; ++ai) _Pragma("unroll") for (int m = 0; m < 4; ++m) _Pragma("unroll") for (int bj = 0; bj < 2; ++bj)
; __device__ __forceinline__ void gemm_up_phase(const bf16_t* a, const bf16_t* wgu, bf16_t* act, char* lds) {
;   gemm_phase(a, 1024, wgu, 1024, 1024, NGU / 256, lds, [&](f32x4 (&acc)[2][2][4][2], int tm, int tn) {
;     GEMM_LANE;
;     GEMM_EPI_LOOP {
;       const int row = tm * 256 + ai * 128 + wr * 64 + m * 16 + fr;
;       const int col = tn * 128 + bj * 64 + wc * 16 + 4 * fq;
;       const f32x4 g = acc[ai][bj][m][0], u = acc[ai][bj][m][1];
;       u32x2 o; o.x = pk2(silu_f(g[0]) * u[0], silu_f(g[1]) * u[1]); o.y = pk2(silu_f(g[2]) * u[2], silu_f(g[3]) * u[3]);
;       *(u32x2*)(act + (size_t)row * DFF + col) = o;
;     }
;   });
	v_rcp_f32_e32 v89, v89
	s_nop 0
	v_pk_mul_f32 v[84:85], v[84:85], v[88:89]
	s_nop 0
	v_pk_mul_f32 v[80:81], v[80:81], v[84:85]
	s_nop 0
	v_cvt_pk_bf16_f32 v80, v80, v81
	v_mul_f32_e32 v81, 0xbfb8aa3b, v86
	v_exp_f32_e32 v81, v81
	s_nop 0
	v_add_f32_e32 v81, 1.0, v81
	v_rcp_f32_e32 v84, v81
	v_mul_f32_e32 v81, 0xbfb8aa3b, v87
	v_exp_f32_e32 v81, v81
	s_nop 0
	v_add_f32_e32 v81, 1.0, v81
	v_rcp_f32_e32 v85, v81
	s_nop 0
	v_pk_mul_f32 v[84:85], v[86:87], v[84:85]
	s_nop 0
	v_pk_mul_f32 v[82:83], v[82:83], v[84:85]
	s_nop 0
	v_cvt_pk_bf16_f32 v81, v82, v83
	v_mov_b32_e32 v150, v80
	v_mov_b32_e32 v151, v81
	s_nop 1
	v_permlane16_swap_b32_e32 v148, v150
	v_permlane16_swap_b32_e32 v149, v151
	global_store_dwordx4 v[90:91], v[148:151], off
	v_mul_f32_e32 v80, 0xbfb8aa3b, v76
	v_mul_f32_e32 v81, 0xbfb8aa3b, v77
	v_exp_f32_e32 v80, v80
	v_exp_f32_e32 v81, v81
	v_or_b32_e32 v82, 48, v128
	v_add_f32_e32 v80, 1.0, v80
	v_add_f32_e32 v81, 1.0, v81
	v_rcp_f32_e32 v80, v80
	v_rcp_f32_e32 v81, v81
	s_nop 0
	v_pk_mul_f32 v[76:77], v[76:77], v[80:81]
	s_nop 0
	v_pk_mul_f32 v[72:73], v[72:73], v[76:77]
	s_nop 0
	v_cvt_pk_bf16_f32 v72, v72, v73
	v_mul_f32_e32 v73, 0xbfb8aa3b, v78
	v_exp_f32_e32 v73, v73
	s_nop 0
	v_add_f32_e32 v73, 1.0, v73
	v_rcp_f32_e32 v76, v73
	v_mul_f32_e32 v73, 0xbfb8aa3b, v79
	v_exp_f32_e32 v73, v73
	s_nop 0
	v_add_f32_e32 v73, 1.0, v73
	v_rcp_f32_e32 v77, v73
	s_nop 0
	v_pk_mul_f32 v[76:77], v[78:79], v[76:77]
	s_nop 0
	v_pk_mul_f32 v[74:75], v[74:75], v[76:77]
	s_nop 0
	v_cvt_pk_bf16_f32 v73, v74, v75
	v_mad_i64_i32 v[74:75], s[0:1], v82, s3, v[120:121]
	v_lshl_add_u64 v[74:75], v[74:75], 0, v[122:123]
	v_mov_b32_e32 v152, v72
	v_mov_b32_e32 v153, v73
	v_mul_f32_e32 v72, 0xbfb8aa3b, v68
	v_mul_f32_e32 v73, 0xbfb8aa3b, v69
	v_exp_f32_e32 v72, v72
	v_exp_f32_e32 v73, v73
	v_add_f32_e32 v72, 1.0, v72
	v_add_f32_e32 v73, 1.0, v73
	v_rcp_f32_e32 v72, v72
	v_rcp_f32_e32 v73, v73
	s_nop 0
	v_pk_mul_f32 v[68:69], v[68:69], v[72:73]
	s_nop 0
	v_pk_mul_f32 v[64:65], v[64:65], v[68:69]
	s_nop 0
	v_cvt_pk_bf16_f32 v64, v64, v65
	v_mul_f32_e32 v65, 0xbfb8aa3b, v70
	v_exp_f32_e32 v65, v65
	s_nop 0
	v_add_f32_e32 v65, 1.0, v65
	v_rcp_f32_e32 v68, v65
	v_mul_f32_e32 v65, 0xbfb8aa3b, v71
	v_exp_f32_e32 v65, v65
	s_nop 0
	v_add_f32_e32 v65, 1.0, v65
	v_rcp_f32_e32 v69, v65
	s_nop 0
	v_pk_mul_f32 v[68:69], v[70:71], v[68:69]
	s_nop 0
	v_pk_mul_f32 v[66:67], v[66:67], v[68:69]
	s_nop 0
	v_cvt_pk_bf16_f32 v65, v66, v67
	v_mov_b32_e32 v154, v64
	v_mov_b32_e32 v155, v65
	s_nop 1
	v_permlane16_swap_b32_e32 v152, v154
	v_permlane16_swap_b32_e32 v153, v155
	global_store_dwordx4 v[74:75], v[152:155], off
	v_mul_f32_e32 v64, 0xbfb8aa3b, v60
	v_mul_f32_e32 v65, 0xbfb8aa3b, v61
	v_exp_f32_e32 v64, v64
	v_exp_f32_e32 v65, v65
	v_add_u32_e32 v66, 0x80, v128
	v_add_f32_e32 v64, 1.0, v64
	v_add_f32_e32 v65, 1.0, v65
	v_rcp_f32_e32 v64, v64
	v_rcp_f32_e32 v65, v65
	s_nop 0
	v_pk_mul_f32 v[60:61], v[60:61], v[64:65]
	s_nop 0
	v_pk_mul_f32 v[56:57], v[56:57], v[60:61]
	s_nop 0
	v_cvt_pk_bf16_f32 v56, v56, v57
	v_mul_f32_e32 v57, 0xbfb8aa3b, v62
	v_exp_f32_e32 v57, v57
	s_nop 0
	v_add_f32_e32 v57, 1.0, v57
	v_rcp_f32_e32 v60, v57
	v_mul_f32_e32 v57, 0xbfb8aa3b, v63
	v_exp_f32_e32 v57, v57
	s_nop 0
	v_add_f32_e32 v57, 1.0, v57
	v_rcp_f32_e32 v61, v57
	s_nop 0
	v_pk_mul_f32 v[60:61], v[62:63], v[60:61]
	s_nop 0
	v_pk_mul_f32 v[58:59], v[58:59], v[60:61]
	s_nop 0
	v_cvt_pk_bf16_f32 v57, v58, v59
	v_mad_i64_i32 v[58:59], s[0:1], v66, s3, v[120:121]
	v_lshl_add_u64 v[58:59], v[58:59], 0, v[122:123]
	v_mov_b32_e32 v156, v56
	v_mov_b32_e32 v157, v57
	v_mul_f32_e32 v56, 0xbfb8aa3b, v52
	v_mul_f32_e32 v57, 0xbfb8aa3b, v53
	v_exp_f32_e32 v56, v56
	v_exp_f32_e32 v57, v57
	v_add_f32_e32 v56, 1.0, v56
	v_add_f32_e32 v57, 1.0, v57
	v_rcp_f32_e32 v56, v56
	v_rcp_f32_e32 v57, v57
	s_nop 0
	v_pk_mul_f32 v[52:53], v[52:53], v[56:57]
	s_nop 0
	v_pk_mul_f32 v[48:49], v[48:49], v[52:53]
	s_nop 0
	v_cvt_pk_bf16_f32 v48, v48, v49
	v_mul_f32_e32 v49, 0xbfb8aa3b, v54
	v_exp_f32_e32 v49, v49
	s_nop 0
	v_add_f32_e32 v49, 1.0, v49
	v_rcp_f32_e32 v52, v49
	v_mul_f32_e32 v49, 0xbfb8aa3b, v55
	v_exp_f32_e32 v49, v49
	s_nop 0
	v_add_f32_e32 v49, 1.0, v49
	v_rcp_f32_e32 v53, v49
	s_nop 0
	v_pk_mul_f32 v[52:53], v[54:55], v[52:53]
	s_nop 0
	v_pk_mul_f32 v[50:51], v[50:51], v[52:53]
	s_nop 0
	v_cvt_pk_bf16_f32 v49, v50, v51
	v_mov_b32_e32 v158, v48
	v_mov_b32_e32 v159, v49
	s_nop 1
	v_permlane16_swap_b32_e32 v156, v158
	v_permlane16_swap_b32_e32 v157, v159
	global_store_dwordx4 v[58:59], v[156:159], off
	v_mul_f32_e32 v48, 0xbfb8aa3b, v44
	v_mul_f32_e32 v49, 0xbfb8aa3b, v45
	v_exp_f32_e32 v48, v48
	v_exp_f32_e32 v49, v49
	v_add_u32_e32 v50, 0x90, v128
	v_add_f32_e32 v48, 1.0, v48
	v_add_f32_e32 v49, 1.0, v49
	v_rcp_f32_e32 v48, v48
	v_rcp_f32_e32 v49, v49
	s_nop 0
	v_pk_mul_f32 v[44:45], v[44:45], v[48:49]
	s_nop 0
	v_pk_mul_f32 v[40:41], v[40:41], v[44:45]
	s_nop 0
	v_cvt_pk_bf16_f32 v40, v40, v41
	v_mul_f32_e32 v41, 0xbfb8aa3b, v46
	v_exp_f32_e32 v41, v41
	s_nop 0
	v_add_f32_e32 v41, 1.0, v41
	v_rcp_f32_e32 v44, v41
	v_mul_f32_e32 v41, 0xbfb8aa3b, v47
; __device__ __forceinline__ unsigned pk2(float lo, float hi) { const f32x2v v = {lo, hi}; const bf16x2v r = __builtin_convertvector(v, bf16x2v); return __builtin_bit_cast(unsigned, r); }
; __device__ __forceinline__ float silu_f(float x) { return x * __builtin_amdgcn_rcpf(1.f + __expf(-x)); }
; #define GEMM_EPI_LOOP _Pragma("unroll") for (int ai = 0; ai < 2; ++ai) _Pragma("unroll") for (int m = 0; m < 4; ++m) _Pragma("unroll") for (int bj = 0; bj < 2; ++bj)
; __device__ __forceinline__ void gemm_up_phase(const bf16_t* a, const bf16_t* wgu, bf16_t* act, char* lds) {
;   gemm_phase(a, 1024, wgu, 1024, 1024, NGU / 256, lds, [&](f32x4 (&acc)[2][2][4][2], int tm, int tn) {
;     GEMM_LANE;
;     GEMM_EPI_LOOP {
;       const int row = tm * 256 + ai * 128 + wr * 64 + m * 16 + fr;
;       const int col = tn * 128 + bj * 64 + wc * 16 + 4 * fq;
;       const f32x4 g = acc[ai][bj][m][0], u = acc[ai][bj][m][1];
;       u32x2 o; o.x = pk2(silu_f(g[0]) * u[0], silu_f(g[1]) * u[1]); o.y = pk2(silu_f(g[2]) * u[2], silu_f(g[3]) * u[3]);
;       *(u32x2*)(act + (size_t)row * DFF + col) = o;
;     }
;   });
	v_exp_f32_e32 v41, v41
	s_nop 0
	v_add_f32_e32 v41, 1.0, v41
	v_rcp_f32_e32 v45, v41
	s_nop 0
	v_pk_mul_f32 v[44:45], v[46:47], v[44:45]
	s_nop 0
	v_pk_mul_f32 v[42:43], v[42:43], v[44:45]
	s_nop 0
	v_cvt_pk_bf16_f32 v41, v42, v43
	v_mad_i64_i32 v[42:43], s[0:1], v50, s3, v[120:121]
	v_lshl_add_u64 v[42:43], v[42:43], 0, v[122:123]
	v_mov_b32_e32 v160, v40
	v_mov_b32_e32 v161, v41
	v_mul_f32_e32 v40, 0xbfb8aa3b, v36
	v_mul_f32_e32 v41, 0xbfb8aa3b, v37
	v_exp_f32_e32 v40, v40
	v_exp_f32_e32 v41, v41
	v_add_f32_e32 v40, 1.0, v40
	v_add_f32_e32 v41, 1.0, v41
	v_rcp_f32_e32 v40, v40
	v_rcp_f32_e32 v41, v41
	s_nop 0
	v_pk_mul_f32 v[36:37], v[36:37], v[40:41]
	s_nop 0
	v_pk_mul_f32 v[32:33], v[32:33], v[36:37]
	s_nop 0
	v_cvt_pk_bf16_f32 v32, v32, v33
	v_mul_f32_e32 v33, 0xbfb8aa3b, v38
	v_exp_f32_e32 v33, v33
	s_nop 0
	v_add_f32_e32 v33, 1.0, v33
	v_rcp_f32_e32 v36, v33
	v_mul_f32_e32 v33, 0xbfb8aa3b, v39
	v_exp_f32_e32 v33, v33
	s_nop 0
	v_add_f32_e32 v33, 1.0, v33
	v_rcp_f32_e32 v37, v33
	s_nop 0
	v_pk_mul_f32 v[36:37], v[38:39], v[36:37]
	s_nop 0
	v_pk_mul_f32 v[34:35], v[34:35], v[36:37]
	s_nop 0
	v_cvt_pk_bf16_f32 v33, v34, v35
	v_mov_b32_e32 v162, v32
	v_mov_b32_e32 v163, v33
	s_nop 1
	v_permlane16_swap_b32_e32 v160, v162
	v_permlane16_swap_b32_e32 v161, v163
	global_store_dwordx4 v[42:43], v[160:163], off
	v_mul_f32_e32 v32, 0xbfb8aa3b, v28
	v_mul_f32_e32 v33, 0xbfb8aa3b, v29
	v_exp_f32_e32 v32, v32
	v_exp_f32_e32 v33, v33
	v_add_u32_e32 v34, 0xa0, v128
	v_add_f32_e32 v32, 1.0, v32
	v_add_f32_e32 v33, 1.0, v33
	v_rcp_f32_e32 v32, v32
	v_rcp_f32_e32 v33, v33
	s_nop 0
	v_pk_mul_f32 v[28:29], v[28:29], v[32:33]
	s_nop 0
	v_pk_mul_f32 v[24:25], v[24:25], v[28:29]
	s_nop 0
	v_cvt_pk_bf16_f32 v24, v24, v25
	v_mul_f32_e32 v25, 0xbfb8aa3b, v30
	v_exp_f32_e32 v25, v25
	s_nop 0
	v_add_f32_e32 v25, 1.0, v25
	v_rcp_f32_e32 v28, v25
	v_mul_f32_e32 v25, 0xbfb8aa3b, v31
	v_exp_f32_e32 v25, v25
	s_nop 0
	v_add_f32_e32 v25, 1.0, v25
	v_rcp_f32_e32 v29, v25
	s_nop 0
	v_pk_mul_f32 v[28:29], v[30:31], v[28:29]
	s_nop 0
	v_pk_mul_f32 v[26:27], v[26:27], v[28:29]
	s_nop 0
	v_cvt_pk_bf16_f32 v25, v26, v27
	v_mad_i64_i32 v[26:27], s[0:1], v34, s3, v[120:121]
	v_lshl_add_u64 v[26:27], v[26:27], 0, v[122:123]
	v_mov_b32_e32 v164, v24
	v_mov_b32_e32 v165, v25
	v_mul_f32_e32 v24, 0xbfb8aa3b, v20
	v_mul_f32_e32 v25, 0xbfb8aa3b, v21
	v_exp_f32_e32 v24, v24
	v_exp_f32_e32 v25, v25
	v_add_f32_e32 v24, 1.0, v24
	v_add_f32_e32 v25, 1.0, v25
	v_rcp_f32_e32 v24, v24
	v_rcp_f32_e32 v25, v25
	s_nop 0
	v_pk_mul_f32 v[20:21], v[20:21], v[24:25]
	s_nop 0
	v_pk_mul_f32 v[16:17], v[16:17], v[20:21]
	s_nop 0
	v_cvt_pk_bf16_f32 v16, v16, v17
	v_mul_f32_e32 v17, 0xbfb8aa3b, v22
	v_exp_f32_e32 v17, v17
	s_nop 0
	v_add_f32_e32 v17, 1.0, v17
	v_rcp_f32_e32 v20, v17
	v_mul_f32_e32 v17, 0xbfb8aa3b, v23
	v_exp_f32_e32 v17, v17
	s_nop 0
	v_add_f32_e32 v17, 1.0, v17
	v_rcp_f32_e32 v21, v17
	s_nop 0
	v_pk_mul_f32 v[20:21], v[22:23], v[20:21]
	s_nop 0
	v_pk_mul_f32 v[18:19], v[18:19], v[20:21]
	s_nop 0
	v_cvt_pk_bf16_f32 v17, v18, v19
	v_mov_b32_e32 v166, v16
	v_mov_b32_e32 v167, v17
	s_nop 1
	v_permlane16_swap_b32_e32 v164, v166
	v_permlane16_swap_b32_e32 v165, v167
	global_store_dwordx4 v[26:27], v[164:167], off
	v_mul_f32_e32 v16, 0xbfb8aa3b, v12
	v_mul_f32_e32 v17, 0xbfb8aa3b, v13
	v_exp_f32_e32 v16, v16
	v_exp_f32_e32 v17, v17
	v_add_u32_e32 v18, 0xb0, v128
	v_add_f32_e32 v16, 1.0, v16
	v_add_f32_e32 v17, 1.0, v17
	v_rcp_f32_e32 v16, v16
	v_rcp_f32_e32 v17, v17
	s_nop 0
	v_pk_mul_f32 v[12:13], v[12:13], v[16:17]
	s_nop 0
	v_pk_mul_f32 v[8:9], v[8:9], v[12:13]
	s_nop 0
	v_cvt_pk_bf16_f32 v8, v8, v9
	v_mul_f32_e32 v9, 0xbfb8aa3b, v14
	v_exp_f32_e32 v9, v9
	s_nop 0
	v_add_f32_e32 v9, 1.0, v9
	v_rcp_f32_e32 v12, v9
	v_mul_f32_e32 v9, 0xbfb8aa3b, v15
	v_exp_f32_e32 v9, v9
	s_nop 0
	v_add_f32_e32 v9, 1.0, v9
	v_rcp_f32_e32 v13, v9
	s_nop 0
	v_pk_mul_f32 v[12:13], v[14:15], v[12:13]
	s_nop 0
	v_pk_mul_f32 v[10:11], v[10:11], v[12:13]
	s_nop 0
	v_cvt_pk_bf16_f32 v9, v10, v11
	v_mad_i64_i32 v[10:11], s[0:1], v18, s3, v[120:121]
	v_lshl_add_u64 v[10:11], v[10:11], 0, v[122:123]
	v_mov_b32_e32 v168, v8
	v_mov_b32_e32 v169, v9
	v_mul_f32_e32 v8, 0xbfb8aa3b, v4
	v_mul_f32_e32 v9, 0xbfb8aa3b, v5
	v_exp_f32_e32 v8, v8
	v_exp_f32_e32 v9, v9
	s_mov_b32 s0, s30
	v_add_f32_e32 v8, 1.0, v8
	v_add_f32_e32 v9, 1.0, v9
	v_rcp_f32_e32 v8, v8
	v_rcp_f32_e32 v9, v9
	s_nop 0
	v_pk_mul_f32 v[4:5], v[4:5], v[8:9]
	s_nop 0
	v_pk_mul_f32 v[0:1], v[0:1], v[4:5]
	s_nop 0
	v_cvt_pk_bf16_f32 v0, v0, v1
	v_mul_f32_e32 v1, 0xbfb8aa3b, v6
	v_exp_f32_e32 v1, v1
	s_nop 0
	v_add_f32_e32 v1, 1.0, v1
	v_rcp_f32_e32 v4, v1
	v_mul_f32_e32 v1, 0xbfb8aa3b, v7
	v_exp_f32_e32 v1, v1
	s_nop 0
	v_add_f32_e32 v1, 1.0, v1
	v_rcp_f32_e32 v5, v1
	s_nop 0
	v_pk_mul_f32 v[4:5], v[6:7], v[4:5]
	s_nop 0
	v_pk_mul_f32 v[2:3], v[2:3], v[4:5]
	s_nop 0
	v_cvt_pk_bf16_f32 v1, v2, v3
	v_mov_b32_e32 v170, v0
	v_mov_b32_e32 v171, v1
	s_nop 1
	v_permlane16_swap_b32_e32 v168, v170
	v_permlane16_swap_b32_e32 v169, v171
	global_store_dwordx4 v[10:11], v[168:171], off
	s_nop 1
	s_cbranch_vccz .LBB0_660
